# speedup vs baseline: 1.0206x; 1.0103x over previous
.LBB0_167:
	v_lshl_add_u64 v[4:5], v[2:3], 0, s[0:1]
	v_add_co_u32_e32 v10, vcc, 0x20001000, v4
	s_nop 1
	v_addc_co_u32_e32 v11, vcc, 0, v5, vcc
	global_load_ushort v42, v[10:11], off
	v_add_co_u32_e32 v12, vcc, 0x20002000, v4
	s_nop 1
	v_addc_co_u32_e32 v13, vcc, 0, v5, vcc
	global_load_ushort v43, v[12:13], off offset:2048
	v_add_co_u32_e32 v14, vcc, 0x20004000, v4
	s_nop 1
	v_addc_co_u32_e32 v15, vcc, 0, v5, vcc
	global_load_ushort v44, v[14:15], off
	v_add_co_u32_e32 v16, vcc, 0x20005000, v4
	s_nop 1
	v_addc_co_u32_e32 v17, vcc, 0, v5, vcc
	global_load_ushort v45, v[16:17], off offset:2048
	v_add_co_u32_e32 v18, vcc, 0x20007000, v4
	s_nop 1
	v_addc_co_u32_e32 v19, vcc, 0, v5, vcc
	global_load_ushort v46, v[18:19], off
	v_add_co_u32_e32 v20, vcc, 0x20008000, v4
	s_nop 1
	v_addc_co_u32_e32 v21, vcc, 0, v5, vcc
	global_load_ushort v47, v[20:21], off offset:2048
	v_add_co_u32_e32 v22, vcc, 0x2000a000, v4
	s_nop 1
	v_addc_co_u32_e32 v23, vcc, 0, v5, vcc
	global_load_ushort v48, v[22:23], off
	v_add_co_u32_e32 v24, vcc, 0x2000b000, v4
	s_nop 1
	v_addc_co_u32_e32 v25, vcc, 0, v5, vcc
	global_load_ushort v49, v[24:25], off offset:2048
	v_add_co_u32_e32 v26, vcc, 0x2000d000, v4
	s_nop 1
	v_addc_co_u32_e32 v27, vcc, 0, v5, vcc
	global_load_ushort v50, v[26:27], off
	v_add_co_u32_e32 v28, vcc, 0x2000e000, v4
	s_nop 1
	v_addc_co_u32_e32 v29, vcc, 0, v5, vcc
	global_load_ushort v51, v[28:29], off offset:2048
	v_add_co_u32_e32 v30, vcc, 0x20010000, v4
	s_nop 1
	v_addc_co_u32_e32 v31, vcc, 0, v5, vcc
	global_load_ushort v52, v[30:31], off
	v_add_co_u32_e32 v32, vcc, 0x20011000, v4
	s_nop 1
	v_addc_co_u32_e32 v33, vcc, 0, v5, vcc
	global_load_ushort v53, v[32:33], off offset:2048
	v_add_co_u32_e32 v34, vcc, 0x20013000, v4
	s_nop 1
	v_addc_co_u32_e32 v35, vcc, 0, v5, vcc
	global_load_ushort v54, v[34:35], off
	v_add_co_u32_e32 v36, vcc, 0x20014000, v4
	s_nop 1
	v_addc_co_u32_e32 v37, vcc, 0, v5, vcc
	global_load_ushort v55, v[36:37], off offset:2048
	v_add_co_u32_e32 v38, vcc, 0x20016000, v4
	s_nop 1
	v_addc_co_u32_e32 v39, vcc, 0, v5, vcc
	global_load_ushort v56, v[38:39], off
	v_add_co_u32_e32 v40, vcc, 0x20017000, v4
	s_nop 1
	v_addc_co_u32_e32 v41, vcc, 0, v5, vcc
	global_load_ushort v57, v[40:41], off offset:2048
	s_add_u32 s0, s0, 0x18000
	s_addc_u32 s1, s1, 0
	s_waitcnt vmcnt(15)
	v_lshlrev_b32_e32 v42, 16, v42
	v_add_f32_e32 v6, v6, v42
	s_waitcnt vmcnt(14)
	v_lshlrev_b32_e32 v43, 16, v43
	v_add_f32_e32 v6, v6, v43
	s_waitcnt vmcnt(13)
	v_lshlrev_b32_e32 v44, 16, v44
	v_add_f32_e32 v6, v6, v44
	s_waitcnt vmcnt(12)
	v_lshlrev_b32_e32 v45, 16, v45
	v_add_f32_e32 v6, v6, v45
	s_waitcnt vmcnt(11)
	v_lshlrev_b32_e32 v46, 16, v46
	v_add_f32_e32 v6, v6, v46
	s_waitcnt vmcnt(10)
	v_lshlrev_b32_e32 v47, 16, v47
	v_add_f32_e32 v6, v6, v47
	s_waitcnt vmcnt(9)
	v_lshlrev_b32_e32 v48, 16, v48
	v_add_f32_e32 v6, v6, v48
	s_waitcnt vmcnt(8)
	v_lshlrev_b32_e32 v49, 16, v49
	v_add_f32_e32 v6, v6, v49
	s_waitcnt vmcnt(7)
	v_lshlrev_b32_e32 v50, 16, v50
	v_add_f32_e32 v6, v6, v50
	s_waitcnt vmcnt(6)
	v_lshlrev_b32_e32 v51, 16, v51
	v_add_f32_e32 v6, v6, v51
	s_waitcnt vmcnt(5)
	v_lshlrev_b32_e32 v52, 16, v52
	v_add_f32_e32 v6, v6, v52
	s_waitcnt vmcnt(4)
	v_lshlrev_b32_e32 v53, 16, v53
	v_add_f32_e32 v6, v6, v53
	s_waitcnt vmcnt(3)
	v_lshlrev_b32_e32 v54, 16, v54
	v_add_f32_e32 v6, v6, v54
	s_waitcnt vmcnt(2)
	v_lshlrev_b32_e32 v55, 16, v55
	v_add_f32_e32 v6, v6, v55
	s_waitcnt vmcnt(1)
	v_lshlrev_b32_e32 v56, 16, v56
	v_add_f32_e32 v6, v6, v56
	s_waitcnt vmcnt(0)
	v_lshlrev_b32_e32 v57, 16, v57
	v_add_f32_e32 v6, v6, v57
	s_cmp_eq_u32 s0, 0x60000
	s_cbranch_scc0 .LBB0_167
	v_lshlrev_b32_e32 v2, 2, v1
	v_cmp_gt_u32_e32 vcc, s33, v1
	s_barrier
	ds_write_b32 v2, v6
	s_waitcnt lgkmcnt(0)
	s_barrier
	s_and_saveexec_b64 s[0:1], vcc
	s_cbranch_execz .LBB0_170
	v_lshlrev_b32_e32 v3, 2, v0
	ds_read2st64_b32 v[0:1], v2 offset0:2 offset1:4
	ds_read_b32 v4, v3
	ds_read_b32 v2, v2 offset:1536
	s_ashr_i32 s91, s90, 31
	s_lshl_b64 s[2:3], s[90:91], 9
	v_readlane_b32 s4, v254, 33
	s_waitcnt lgkmcnt(1)
	v_add_f32_e32 v0, v4, v0
	v_add_f32_e32 v0, v0, v1
	s_waitcnt lgkmcnt(0)
	v_add_f32_e32 v0, v0, v2
	s_add_u32 s2, s4, s2
	v_readlane_b32 s4, v254, 34
	v_mul_f32_e32 v0, 0x3b800000, v0
	s_addc_u32 s3, s4, s3
	global_store_dword v3, v0, s[2:3]

.LBB0_260:
	s_andn2_b64 vcc, exec, s[2:3]
	s_cbranch_vccnz .LBB0_430
	s_add_u32 s0, s40, s94
	v_add_u32_e32 v132, s91, v157
	s_addc_u32 s1, s41, s95
	v_lshlrev_b32_e32 v128, 1, v160
	v_ashrrev_i32_e32 v133, 31, v132
	v_lshl_add_u64 v[130:131], s[0:1], 0, v[128:129]
	v_lshlrev_b32_e32 v128, 2, v158
	v_lshlrev_b64 v[132:133], 12, v[132:133]
	v_bitop3_b32 v145, v128, 64, v155 bitop3:0x6c
	v_bitop3_b32 v144, v128, s33, v155 bitop3:0x6c
	v_cmp_eq_u32_e32 vcc, 0, v135
	v_lshlrev_b32_e32 v128, 3, v134
	v_lshl_add_u64 v[134:135], v[130:131], 0, v[132:133]
	v_mov_b32_e32 v237, v129
	v_add_u32_e32 v236, s91, v157
	v_lshlrev_b32_e32 v236, 12, v236
	v_lshl_add_u64 v[234:235], v[130:131], 0, v[236:237]
	global_load_dwordx2 v[170:171], v[234:235], off
	global_load_dwordx2 v[172:173], v[234:235], off offset:32
	global_load_dwordx2 v[174:175], v[234:235], off offset:256
	global_load_dwordx2 v[176:177], v[234:235], off offset:288
	v_add_u32_e32 v236, s91, v157
	v_add_u32_e32 v236, 0x10, v236
	v_lshlrev_b32_e32 v236, 12, v236
	v_lshl_add_u64 v[234:235], v[130:131], 0, v[236:237]
	global_load_dwordx2 v[178:179], v[234:235], off
	global_load_dwordx2 v[180:181], v[234:235], off offset:32
	global_load_dwordx2 v[182:183], v[234:235], off offset:256
	global_load_dwordx2 v[184:185], v[234:235], off offset:288
	v_add_u32_e32 v236, s91, v157
	v_add_u32_e32 v236, 0x20, v236
	v_lshlrev_b32_e32 v236, 12, v236
	v_lshl_add_u64 v[234:235], v[130:131], 0, v[236:237]
	global_load_dwordx2 v[186:187], v[234:235], off
	global_load_dwordx2 v[188:189], v[234:235], off offset:32
	global_load_dwordx2 v[190:191], v[234:235], off offset:256
	global_load_dwordx2 v[192:193], v[234:235], off offset:288
	v_add_u32_e32 v236, s91, v157
	v_add_u32_e32 v236, 0x30, v236
	v_lshlrev_b32_e32 v236, 12, v236
	v_lshl_add_u64 v[234:235], v[130:131], 0, v[236:237]
	global_load_dwordx2 v[194:195], v[234:235], off
	global_load_dwordx2 v[196:197], v[234:235], off offset:32
	global_load_dwordx2 v[198:199], v[234:235], off offset:256
	global_load_dwordx2 v[200:201], v[234:235], off offset:288
	v_add_u32_e32 v236, s91, v157
	v_add_u32_e32 v236, 0x80, v236
	v_lshlrev_b32_e32 v236, 12, v236
	v_lshl_add_u64 v[234:235], v[130:131], 0, v[236:237]
	global_load_dwordx2 v[202:203], v[234:235], off
	global_load_dwordx2 v[204:205], v[234:235], off offset:32
	global_load_dwordx2 v[206:207], v[234:235], off offset:256
	global_load_dwordx2 v[208:209], v[234:235], off offset:288
	v_add_u32_e32 v236, s91, v157
	v_add_u32_e32 v236, 0x90, v236
	v_lshlrev_b32_e32 v236, 12, v236
	v_lshl_add_u64 v[234:235], v[130:131], 0, v[236:237]
	global_load_dwordx2 v[210:211], v[234:235], off
	global_load_dwordx2 v[212:213], v[234:235], off offset:32
	global_load_dwordx2 v[214:215], v[234:235], off offset:256
	global_load_dwordx2 v[216:217], v[234:235], off offset:288
	v_add_u32_e32 v236, s91, v157
	v_add_u32_e32 v236, 0xa0, v236
	v_lshlrev_b32_e32 v236, 12, v236
	v_lshl_add_u64 v[234:235], v[130:131], 0, v[236:237]
	global_load_dwordx2 v[218:219], v[234:235], off
	global_load_dwordx2 v[220:221], v[234:235], off offset:32
	global_load_dwordx2 v[222:223], v[234:235], off offset:256
	global_load_dwordx2 v[224:225], v[234:235], off offset:288
	v_add_u32_e32 v236, s91, v157
	v_add_u32_e32 v236, 0xb0, v236
	v_lshlrev_b32_e32 v236, 12, v236
	v_lshl_add_u64 v[234:235], v[130:131], 0, v[236:237]
	global_load_dwordx2 v[226:227], v[234:235], off
	global_load_dwordx2 v[228:229], v[234:235], off offset:32
	global_load_dwordx2 v[230:231], v[234:235], off offset:256
	global_load_dwordx2 v[232:233], v[234:235], off offset:288
	s_waitcnt vmcnt(0)
	v_mov_b32_e32 v132, v170
	v_mov_b32_e32 v133, v171
	s_waitcnt vmcnt(0)
	v_lshlrev_b32_e32 v136, 16, v132
	v_and_b32_e32 v137, 0xffff0000, v132
	v_lshlrev_b32_e32 v132, 16, v133
	v_and_b32_e32 v133, 0xffff0000, v133
	v_pk_fma_f32 v[124:125], v[136:137], s[80:81], v[124:125] op_sel_hi:[1,0,1]
	v_pk_fma_f32 v[126:127], v[132:133], s[80:81], v[126:127] op_sel_hi:[1,0,1]
	v_mov_b32_e32 v132, v124
	v_mov_b32_e32 v133, v126
	v_mov_b32_e32 v136, v125
	v_mov_b32_e32 v137, v127
	v_pk_add_f32 v[132:133], v[132:133], v[136:137]
	s_waitcnt vmcnt(0)
	v_mov_b32_e32 v136, v172
	v_mov_b32_e32 v137, v173
	v_fma_f32 v146, v127, v127, 0
	v_fmac_f32_e32 v146, v126, v126
	v_fmac_f32_e32 v146, v125, v125
	v_fmac_f32_e32 v146, v124, v124
	v_add_f32_e32 v132, v132, v133
	v_add_f32_e32 v132, 0, v132
	s_waitcnt vmcnt(0)
	v_lshlrev_b32_e32 v138, 16, v136
	v_and_b32_e32 v139, 0xffff0000, v136
	v_lshlrev_b32_e32 v136, 16, v137
	v_and_b32_e32 v137, 0xffff0000, v137
	v_pk_fma_f32 v[120:121], v[138:139], s[80:81], v[120:121] op_sel_hi:[1,0,1]
	v_pk_fma_f32 v[122:123], v[136:137], s[80:81], v[122:123] op_sel_hi:[1,0,1]
	v_mov_b32_e32 v136, v120
	v_mov_b32_e32 v137, v122
	v_mov_b32_e32 v138, v121
	v_mov_b32_e32 v139, v123
	v_pk_add_f32 v[136:137], v[136:137], v[138:139]
	s_waitcnt vmcnt(0)
	v_mov_b32_e32 v138, v174
	v_mov_b32_e32 v139, v175
	v_fmac_f32_e32 v146, v123, v123
	s_waitcnt vmcnt(0)
	v_mov_b32_e32 v134, v176
	v_mov_b32_e32 v135, v177
	v_fmac_f32_e32 v146, v122, v122
	v_fmac_f32_e32 v146, v121, v121
	v_fmac_f32_e32 v146, v120, v120
	v_pk_add_f32 v[136:137], v[136:137], v[136:137] op_sel:[0,1] op_sel_hi:[1,0]
	s_waitcnt vmcnt(1)
	v_lshlrev_b32_e32 v140, 16, v138
	v_and_b32_e32 v141, 0xffff0000, v138
	v_lshlrev_b32_e32 v138, 16, v139
	v_and_b32_e32 v139, 0xffff0000, v139
	v_pk_fma_f32 v[118:119], v[138:139], s[80:81], v[118:119] op_sel_hi:[1,0,1]
	v_pk_fma_f32 v[116:117], v[140:141], s[80:81], v[116:117] op_sel_hi:[1,0,1]
	v_fmac_f32_e32 v146, v119, v119
	v_fmac_f32_e32 v146, v118, v118
	v_fmac_f32_e32 v146, v117, v117
	s_waitcnt vmcnt(0)
	v_lshlrev_b32_e32 v142, 16, v134
	v_and_b32_e32 v143, 0xffff0000, v134
	v_lshlrev_b32_e32 v134, 16, v135
	v_and_b32_e32 v135, 0xffff0000, v135
	v_pk_add_f32 v[138:139], v[116:117], v[116:117] op_sel:[0,1] op_sel_hi:[1,0]
	v_pk_add_f32 v[140:141], v[118:119], v[118:119] op_sel:[0,1] op_sel_hi:[1,0]
	v_fmac_f32_e32 v146, v116, v116
	v_pk_fma_f32 v[112:113], v[142:143], s[80:81], v[112:113] op_sel_hi:[1,0,1]
	v_pk_fma_f32 v[114:115], v[134:135], s[80:81], v[114:115] op_sel_hi:[1,0,1]
	v_mov_b32_e32 v133, v112
	v_mov_b32_e32 v137, v113
	v_mov_b32_e32 v139, v114
	v_mov_b32_e32 v141, v115
	v_fmac_f32_e32 v146, v115, v115
	v_pk_add_f32 v[132:133], v[132:133], v[136:137]
	v_pk_add_f32 v[134:135], v[138:139], v[140:141]
	v_fmac_f32_e32 v146, v114, v114
	v_pk_add_f32 v[132:133], v[132:133], v[134:135]
	v_fmac_f32_e32 v146, v113, v113
	v_pk_add_f32 v[132:133], v[132:133], v[132:133] op_sel:[0,1] op_sel_hi:[1,0]
	v_fmac_f32_e32 v146, v112, v112
	ds_bpermute_b32 v134, v145, v132
	ds_bpermute_b32 v135, v145, v146
	v_mov_b32_e32 v133, v146
	s_waitcnt lgkmcnt(0)
	v_pk_add_f32 v[132:133], v[132:133], v[134:135]
	ds_bpermute_b32 v134, v144, v132
	ds_bpermute_b32 v135, v144, v133
	s_and_saveexec_b64 s[0:1], vcc
	s_cbranch_execz .LBB0_263
	v_lshl_or_b32 v136, v157, 5, v128
	s_waitcnt lgkmcnt(0)
	v_pk_add_f32 v[132:133], v[132:133], v[134:135]
	ds_write_b64 v136, v[132:133]
.LBB0_263:
	s_or_b64 exec, exec, s[0:1]
	v_or_b32_e32 v161, 16, v157
	v_add_u32_e32 v132, s91, v161
	v_ashrrev_i32_e32 v133, 31, v132
	v_lshlrev_b64 v[132:133], 12, v[132:133]
	s_waitcnt lgkmcnt(0)
	v_lshl_add_u64 v[134:135], v[130:131], 0, v[132:133]
	s_waitcnt vmcnt(0)
	v_mov_b32_e32 v132, v178
	v_mov_b32_e32 v133, v179
	s_waitcnt vmcnt(0)
	v_lshlrev_b32_e32 v136, 16, v132
	v_and_b32_e32 v137, 0xffff0000, v132
	v_lshlrev_b32_e32 v132, 16, v133
	v_and_b32_e32 v133, 0xffff0000, v133
	v_pk_fma_f32 v[108:109], v[136:137], s[80:81], v[108:109] op_sel_hi:[1,0,1]
	v_pk_fma_f32 v[110:111], v[132:133], s[80:81], v[110:111] op_sel_hi:[1,0,1]
	v_mov_b32_e32 v132, v108
	v_mov_b32_e32 v133, v110
	v_mov_b32_e32 v136, v109
	v_mov_b32_e32 v137, v111
	v_pk_add_f32 v[132:133], v[132:133], v[136:137]
	s_waitcnt vmcnt(0)
	v_mov_b32_e32 v136, v180
	v_mov_b32_e32 v137, v181
	v_fma_f32 v146, v111, v111, 0
	v_fmac_f32_e32 v146, v110, v110
	v_fmac_f32_e32 v146, v109, v109
	v_fmac_f32_e32 v146, v108, v108
	v_add_f32_e32 v132, v132, v133
	v_add_f32_e32 v132, 0, v132
	s_waitcnt vmcnt(0)
	v_lshlrev_b32_e32 v138, 16, v136
	v_and_b32_e32 v139, 0xffff0000, v136
	v_lshlrev_b32_e32 v136, 16, v137
	v_and_b32_e32 v137, 0xffff0000, v137
	v_pk_fma_f32 v[104:105], v[138:139], s[80:81], v[104:105] op_sel_hi:[1,0,1]
	v_pk_fma_f32 v[106:107], v[136:137], s[80:81], v[106:107] op_sel_hi:[1,0,1]
	v_mov_b32_e32 v136, v104
	v_mov_b32_e32 v137, v106
	v_mov_b32_e32 v138, v105
	v_mov_b32_e32 v139, v107
	v_pk_add_f32 v[136:137], v[136:137], v[138:139]
	s_waitcnt vmcnt(0)
	v_mov_b32_e32 v138, v182
	v_mov_b32_e32 v139, v183
	v_fmac_f32_e32 v146, v107, v107
	s_waitcnt vmcnt(0)
	v_mov_b32_e32 v134, v184
	v_mov_b32_e32 v135, v185
	v_fmac_f32_e32 v146, v106, v106
	v_fmac_f32_e32 v146, v105, v105
	v_fmac_f32_e32 v146, v104, v104
	v_pk_add_f32 v[136:137], v[136:137], v[136:137] op_sel:[0,1] op_sel_hi:[1,0]
	s_waitcnt vmcnt(1)
	v_lshlrev_b32_e32 v140, 16, v138
	v_and_b32_e32 v141, 0xffff0000, v138
	v_lshlrev_b32_e32 v138, 16, v139
	v_and_b32_e32 v139, 0xffff0000, v139
	v_pk_fma_f32 v[102:103], v[138:139], s[80:81], v[102:103] op_sel_hi:[1,0,1]
	v_pk_fma_f32 v[100:101], v[140:141], s[80:81], v[100:101] op_sel_hi:[1,0,1]
	v_fmac_f32_e32 v146, v103, v103
	v_fmac_f32_e32 v146, v102, v102
	v_fmac_f32_e32 v146, v101, v101
	s_waitcnt vmcnt(0)
	v_lshlrev_b32_e32 v142, 16, v134
	v_and_b32_e32 v143, 0xffff0000, v134
	v_lshlrev_b32_e32 v134, 16, v135
	v_and_b32_e32 v135, 0xffff0000, v135
	v_pk_add_f32 v[138:139], v[100:101], v[100:101] op_sel:[0,1] op_sel_hi:[1,0]
	v_pk_add_f32 v[140:141], v[102:103], v[102:103] op_sel:[0,1] op_sel_hi:[1,0]
	v_fmac_f32_e32 v146, v100, v100
	v_pk_fma_f32 v[96:97], v[142:143], s[80:81], v[96:97] op_sel_hi:[1,0,1]
	v_pk_fma_f32 v[98:99], v[134:135], s[80:81], v[98:99] op_sel_hi:[1,0,1]
	v_mov_b32_e32 v133, v96
	v_mov_b32_e32 v137, v97
	v_mov_b32_e32 v139, v98
	v_mov_b32_e32 v141, v99
	v_fmac_f32_e32 v146, v99, v99
	v_pk_add_f32 v[132:133], v[132:133], v[136:137]
	v_pk_add_f32 v[134:135], v[138:139], v[140:141]
	v_fmac_f32_e32 v146, v98, v98
	v_pk_add_f32 v[132:133], v[132:133], v[134:135]
	v_fmac_f32_e32 v146, v97, v97
	v_pk_add_f32 v[132:133], v[132:133], v[132:133] op_sel:[0,1] op_sel_hi:[1,0]
	v_fmac_f32_e32 v146, v96, v96
	ds_bpermute_b32 v134, v145, v132
	ds_bpermute_b32 v135, v145, v146
	v_mov_b32_e32 v133, v146
	s_waitcnt lgkmcnt(0)
	v_pk_add_f32 v[132:133], v[132:133], v[134:135]
	ds_bpermute_b32 v134, v144, v132
	ds_bpermute_b32 v135, v144, v133
	s_and_saveexec_b64 s[0:1], vcc
	s_cbranch_execz .LBB0_265
	v_lshl_or_b32 v136, v161, 5, v128
	s_waitcnt lgkmcnt(0)
	v_pk_add_f32 v[132:133], v[132:133], v[134:135]
	ds_write_b64 v136, v[132:133]
.LBB0_265:
	s_or_b64 exec, exec, s[0:1]
	v_or_b32_e32 v162, 32, v157
	v_add_u32_e32 v132, s91, v162
	v_ashrrev_i32_e32 v133, 31, v132
	v_lshlrev_b64 v[132:133], 12, v[132:133]
	s_waitcnt lgkmcnt(0)
	v_lshl_add_u64 v[134:135], v[130:131], 0, v[132:133]
	s_waitcnt vmcnt(0)
	v_mov_b32_e32 v132, v186
	v_mov_b32_e32 v133, v187
	s_waitcnt vmcnt(0)
	v_lshlrev_b32_e32 v136, 16, v132
	v_and_b32_e32 v137, 0xffff0000, v132
	v_lshlrev_b32_e32 v132, 16, v133
	v_and_b32_e32 v133, 0xffff0000, v133
	v_pk_fma_f32 v[92:93], v[136:137], s[80:81], v[92:93] op_sel_hi:[1,0,1]
	v_pk_fma_f32 v[94:95], v[132:133], s[80:81], v[94:95] op_sel_hi:[1,0,1]
	v_mov_b32_e32 v132, v92
	v_mov_b32_e32 v133, v94
	v_mov_b32_e32 v136, v93
	v_mov_b32_e32 v137, v95
	v_pk_add_f32 v[132:133], v[132:133], v[136:137]
	s_waitcnt vmcnt(0)
	v_mov_b32_e32 v136, v188
	v_mov_b32_e32 v137, v189
	v_fma_f32 v146, v95, v95, 0
	v_fmac_f32_e32 v146, v94, v94
	v_fmac_f32_e32 v146, v93, v93
	v_fmac_f32_e32 v146, v92, v92
	v_add_f32_e32 v132, v132, v133
	v_add_f32_e32 v132, 0, v132
	s_waitcnt vmcnt(0)
	v_lshlrev_b32_e32 v138, 16, v136
	v_and_b32_e32 v139, 0xffff0000, v136
	v_lshlrev_b32_e32 v136, 16, v137
	v_and_b32_e32 v137, 0xffff0000, v137
	v_pk_fma_f32 v[88:89], v[138:139], s[80:81], v[88:89] op_sel_hi:[1,0,1]
	v_pk_fma_f32 v[90:91], v[136:137], s[80:81], v[90:91] op_sel_hi:[1,0,1]
	v_mov_b32_e32 v136, v88
	v_mov_b32_e32 v137, v90
	v_mov_b32_e32 v138, v89
	v_mov_b32_e32 v139, v91
	v_pk_add_f32 v[136:137], v[136:137], v[138:139]
	s_waitcnt vmcnt(0)
	v_mov_b32_e32 v138, v190
	v_mov_b32_e32 v139, v191
	v_fmac_f32_e32 v146, v91, v91
	s_waitcnt vmcnt(0)
	v_mov_b32_e32 v134, v192
	v_mov_b32_e32 v135, v193
	v_fmac_f32_e32 v146, v90, v90
	v_fmac_f32_e32 v146, v89, v89
	v_fmac_f32_e32 v146, v88, v88
	v_pk_add_f32 v[136:137], v[136:137], v[136:137] op_sel:[0,1] op_sel_hi:[1,0]
	s_waitcnt vmcnt(1)
	v_lshlrev_b32_e32 v140, 16, v138
	v_and_b32_e32 v141, 0xffff0000, v138
	v_lshlrev_b32_e32 v138, 16, v139
	v_and_b32_e32 v139, 0xffff0000, v139
	v_pk_fma_f32 v[86:87], v[138:139], s[80:81], v[86:87] op_sel_hi:[1,0,1]
	v_pk_fma_f32 v[84:85], v[140:141], s[80:81], v[84:85] op_sel_hi:[1,0,1]
	v_fmac_f32_e32 v146, v87, v87
	v_fmac_f32_e32 v146, v86, v86
	v_fmac_f32_e32 v146, v85, v85
	s_waitcnt vmcnt(0)
	v_lshlrev_b32_e32 v142, 16, v134
	v_and_b32_e32 v143, 0xffff0000, v134
	v_lshlrev_b32_e32 v134, 16, v135
	v_and_b32_e32 v135, 0xffff0000, v135
	v_pk_add_f32 v[138:139], v[84:85], v[84:85] op_sel:[0,1] op_sel_hi:[1,0]
	v_pk_add_f32 v[140:141], v[86:87], v[86:87] op_sel:[0,1] op_sel_hi:[1,0]
	v_fmac_f32_e32 v146, v84, v84
	v_pk_fma_f32 v[80:81], v[142:143], s[80:81], v[80:81] op_sel_hi:[1,0,1]
	v_pk_fma_f32 v[82:83], v[134:135], s[80:81], v[82:83] op_sel_hi:[1,0,1]
	v_mov_b32_e32 v133, v80
	v_mov_b32_e32 v137, v81
	v_mov_b32_e32 v139, v82
	v_mov_b32_e32 v141, v83
	v_fmac_f32_e32 v146, v83, v83
	v_pk_add_f32 v[132:133], v[132:133], v[136:137]
	v_pk_add_f32 v[134:135], v[138:139], v[140:141]
	v_fmac_f32_e32 v146, v82, v82
	v_pk_add_f32 v[132:133], v[132:133], v[134:135]
	v_fmac_f32_e32 v146, v81, v81
	v_pk_add_f32 v[132:133], v[132:133], v[132:133] op_sel:[0,1] op_sel_hi:[1,0]
	v_fmac_f32_e32 v146, v80, v80
	ds_bpermute_b32 v134, v145, v132
	ds_bpermute_b32 v135, v145, v146
	v_mov_b32_e32 v133, v146
	s_waitcnt lgkmcnt(0)
	v_pk_add_f32 v[132:133], v[132:133], v[134:135]
	ds_bpermute_b32 v134, v144, v132
	ds_bpermute_b32 v135, v144, v133
	s_and_saveexec_b64 s[0:1], vcc
	s_cbranch_execz .LBB0_267
	v_lshl_or_b32 v136, v162, 5, v128
	s_waitcnt lgkmcnt(0)
	v_pk_add_f32 v[132:133], v[132:133], v[134:135]
	ds_write_b64 v136, v[132:133]
.LBB0_267:
	s_or_b64 exec, exec, s[0:1]
	v_or_b32_e32 v163, 48, v157
	v_add_u32_e32 v132, s91, v163
	v_ashrrev_i32_e32 v133, 31, v132
	v_lshlrev_b64 v[132:133], 12, v[132:133]
	s_waitcnt lgkmcnt(0)
	v_lshl_add_u64 v[134:135], v[130:131], 0, v[132:133]
	s_waitcnt vmcnt(0)
	v_mov_b32_e32 v132, v194
	v_mov_b32_e32 v133, v195
	s_waitcnt vmcnt(0)
	v_lshlrev_b32_e32 v136, 16, v132
	v_and_b32_e32 v137, 0xffff0000, v132
	v_lshlrev_b32_e32 v132, 16, v133
	v_and_b32_e32 v133, 0xffff0000, v133
	v_pk_fma_f32 v[76:77], v[136:137], s[80:81], v[76:77] op_sel_hi:[1,0,1]
	v_pk_fma_f32 v[78:79], v[132:133], s[80:81], v[78:79] op_sel_hi:[1,0,1]
	v_mov_b32_e32 v132, v76
	v_mov_b32_e32 v133, v78
	v_mov_b32_e32 v136, v77
	v_mov_b32_e32 v137, v79
	v_pk_add_f32 v[132:133], v[132:133], v[136:137]
	s_waitcnt vmcnt(0)
	v_mov_b32_e32 v136, v196
	v_mov_b32_e32 v137, v197
	v_fma_f32 v146, v79, v79, 0
	v_fmac_f32_e32 v146, v78, v78
	v_fmac_f32_e32 v146, v77, v77
	v_fmac_f32_e32 v146, v76, v76
	v_add_f32_e32 v132, v132, v133
	v_add_f32_e32 v132, 0, v132
	s_waitcnt vmcnt(0)
	v_lshlrev_b32_e32 v138, 16, v136
	v_and_b32_e32 v139, 0xffff0000, v136
	v_lshlrev_b32_e32 v136, 16, v137
	v_and_b32_e32 v137, 0xffff0000, v137
	v_pk_fma_f32 v[72:73], v[138:139], s[80:81], v[72:73] op_sel_hi:[1,0,1]
	v_pk_fma_f32 v[74:75], v[136:137], s[80:81], v[74:75] op_sel_hi:[1,0,1]
	v_mov_b32_e32 v136, v72
	v_mov_b32_e32 v137, v74
	v_mov_b32_e32 v138, v73
	v_mov_b32_e32 v139, v75
	v_pk_add_f32 v[136:137], v[136:137], v[138:139]
	s_waitcnt vmcnt(0)
	v_mov_b32_e32 v138, v198
	v_mov_b32_e32 v139, v199
	v_fmac_f32_e32 v146, v75, v75
	s_waitcnt vmcnt(0)
	v_mov_b32_e32 v134, v200
	v_mov_b32_e32 v135, v201
	v_fmac_f32_e32 v146, v74, v74
	v_fmac_f32_e32 v146, v73, v73
	v_fmac_f32_e32 v146, v72, v72
	v_pk_add_f32 v[136:137], v[136:137], v[136:137] op_sel:[0,1] op_sel_hi:[1,0]
	s_waitcnt vmcnt(1)
	v_lshlrev_b32_e32 v140, 16, v138
	v_and_b32_e32 v141, 0xffff0000, v138
	v_lshlrev_b32_e32 v138, 16, v139
	v_and_b32_e32 v139, 0xffff0000, v139
	v_pk_fma_f32 v[70:71], v[138:139], s[80:81], v[70:71] op_sel_hi:[1,0,1]
	v_pk_fma_f32 v[68:69], v[140:141], s[80:81], v[68:69] op_sel_hi:[1,0,1]
	v_fmac_f32_e32 v146, v71, v71
	v_fmac_f32_e32 v146, v70, v70
	v_fmac_f32_e32 v146, v69, v69
	s_waitcnt vmcnt(0)
	v_lshlrev_b32_e32 v142, 16, v134
	v_and_b32_e32 v143, 0xffff0000, v134
	v_lshlrev_b32_e32 v134, 16, v135
	v_and_b32_e32 v135, 0xffff0000, v135
	v_pk_add_f32 v[138:139], v[68:69], v[68:69] op_sel:[0,1] op_sel_hi:[1,0]
	v_pk_add_f32 v[140:141], v[70:71], v[70:71] op_sel:[0,1] op_sel_hi:[1,0]
	v_fmac_f32_e32 v146, v68, v68
	v_pk_fma_f32 v[64:65], v[142:143], s[80:81], v[64:65] op_sel_hi:[1,0,1]
	v_pk_fma_f32 v[66:67], v[134:135], s[80:81], v[66:67] op_sel_hi:[1,0,1]
	v_mov_b32_e32 v133, v64
	v_mov_b32_e32 v137, v65
	v_mov_b32_e32 v139, v66
	v_mov_b32_e32 v141, v67
	v_fmac_f32_e32 v146, v67, v67
	v_pk_add_f32 v[132:133], v[132:133], v[136:137]
	v_pk_add_f32 v[134:135], v[138:139], v[140:141]
	v_fmac_f32_e32 v146, v66, v66
	v_pk_add_f32 v[132:133], v[132:133], v[134:135]
	v_fmac_f32_e32 v146, v65, v65
	v_pk_add_f32 v[132:133], v[132:133], v[132:133] op_sel:[0,1] op_sel_hi:[1,0]
	v_fmac_f32_e32 v146, v64, v64
	ds_bpermute_b32 v134, v145, v132
	ds_bpermute_b32 v135, v145, v146
	v_mov_b32_e32 v133, v146
	s_waitcnt lgkmcnt(0)
	v_pk_add_f32 v[132:133], v[132:133], v[134:135]
	ds_bpermute_b32 v134, v144, v132
	ds_bpermute_b32 v135, v144, v133
	s_and_saveexec_b64 s[0:1], vcc
	s_cbranch_execz .LBB0_269
	v_lshl_or_b32 v136, v163, 5, v128
	s_waitcnt lgkmcnt(0)
	v_pk_add_f32 v[132:133], v[132:133], v[134:135]
	ds_write_b64 v136, v[132:133]
.LBB0_269:
	s_or_b64 exec, exec, s[0:1]
	v_add_u32_e32 v136, 0x80, v157
	v_add_u32_e32 v132, s91, v136
	v_ashrrev_i32_e32 v133, 31, v132
	v_lshlrev_b64 v[132:133], 12, v[132:133]
	s_waitcnt lgkmcnt(0)
	v_lshl_add_u64 v[134:135], v[130:131], 0, v[132:133]
	s_waitcnt vmcnt(0)
	v_mov_b32_e32 v132, v202
	v_mov_b32_e32 v133, v203
	s_waitcnt vmcnt(0)
	v_lshlrev_b32_e32 v138, 16, v132
	v_and_b32_e32 v139, 0xffff0000, v132
	v_lshlrev_b32_e32 v132, 16, v133
	v_and_b32_e32 v133, 0xffff0000, v133
	v_pk_fma_f32 v[60:61], v[138:139], s[80:81], v[60:61] op_sel_hi:[1,0,1]
	v_pk_fma_f32 v[62:63], v[132:133], s[80:81], v[62:63] op_sel_hi:[1,0,1]
	v_mov_b32_e32 v132, v60
	v_mov_b32_e32 v133, v62
	v_mov_b32_e32 v138, v61
	v_mov_b32_e32 v139, v63
	v_pk_add_f32 v[132:133], v[132:133], v[138:139]
	s_waitcnt vmcnt(0)
	v_mov_b32_e32 v138, v204
	v_mov_b32_e32 v139, v205
	v_fma_f32 v137, v63, v63, 0
	v_fmac_f32_e32 v137, v62, v62
	v_fmac_f32_e32 v137, v61, v61
	v_fmac_f32_e32 v137, v60, v60
	v_add_f32_e32 v132, v132, v133
	v_add_f32_e32 v132, 0, v132
	s_waitcnt vmcnt(0)
	v_lshlrev_b32_e32 v140, 16, v138
	v_and_b32_e32 v141, 0xffff0000, v138
	v_lshlrev_b32_e32 v138, 16, v139
	v_and_b32_e32 v139, 0xffff0000, v139
	v_pk_fma_f32 v[56:57], v[140:141], s[80:81], v[56:57] op_sel_hi:[1,0,1]
	v_pk_fma_f32 v[58:59], v[138:139], s[80:81], v[58:59] op_sel_hi:[1,0,1]
	v_mov_b32_e32 v138, v56
	v_mov_b32_e32 v139, v58
	v_mov_b32_e32 v140, v57
	v_mov_b32_e32 v141, v59
	v_pk_add_f32 v[138:139], v[138:139], v[140:141]
	s_waitcnt vmcnt(0)
	v_mov_b32_e32 v140, v206
	v_mov_b32_e32 v141, v207
	v_fmac_f32_e32 v137, v59, v59
	s_waitcnt vmcnt(0)
	v_mov_b32_e32 v134, v208
	v_mov_b32_e32 v135, v209
	v_fmac_f32_e32 v137, v58, v58
	v_fmac_f32_e32 v137, v57, v57
	v_fmac_f32_e32 v137, v56, v56
	v_pk_add_f32 v[138:139], v[138:139], v[138:139] op_sel:[0,1] op_sel_hi:[1,0]
	s_waitcnt vmcnt(1)
	v_lshlrev_b32_e32 v142, 16, v140
	v_and_b32_e32 v143, 0xffff0000, v140
	v_lshlrev_b32_e32 v140, 16, v141
	v_and_b32_e32 v141, 0xffff0000, v141
	v_pk_fma_f32 v[54:55], v[140:141], s[80:81], v[54:55] op_sel_hi:[1,0,1]
	v_pk_fma_f32 v[52:53], v[142:143], s[80:81], v[52:53] op_sel_hi:[1,0,1]
	v_fmac_f32_e32 v137, v55, v55
	v_fmac_f32_e32 v137, v54, v54
	v_fmac_f32_e32 v137, v53, v53
	s_waitcnt vmcnt(0)
	v_lshlrev_b32_e32 v150, 16, v134
	v_and_b32_e32 v151, 0xffff0000, v134
	v_lshlrev_b32_e32 v134, 16, v135
	v_and_b32_e32 v135, 0xffff0000, v135
	v_pk_add_f32 v[140:141], v[52:53], v[52:53] op_sel:[0,1] op_sel_hi:[1,0]
	v_pk_add_f32 v[142:143], v[54:55], v[54:55] op_sel:[0,1] op_sel_hi:[1,0]
	v_fmac_f32_e32 v137, v52, v52
	v_pk_fma_f32 v[48:49], v[150:151], s[80:81], v[48:49] op_sel_hi:[1,0,1]
	v_pk_fma_f32 v[50:51], v[134:135], s[80:81], v[50:51] op_sel_hi:[1,0,1]
	v_mov_b32_e32 v133, v48
	v_mov_b32_e32 v139, v49
	v_mov_b32_e32 v141, v50
	v_mov_b32_e32 v143, v51
	v_fmac_f32_e32 v137, v51, v51
	v_pk_add_f32 v[132:133], v[132:133], v[138:139]
	v_pk_add_f32 v[134:135], v[140:141], v[142:143]
	v_fmac_f32_e32 v137, v50, v50
	v_pk_add_f32 v[132:133], v[132:133], v[134:135]
	v_fmac_f32_e32 v137, v49, v49
	v_pk_add_f32 v[132:133], v[132:133], v[132:133] op_sel:[0,1] op_sel_hi:[1,0]
	v_fmac_f32_e32 v137, v48, v48
	ds_bpermute_b32 v134, v145, v132
	ds_bpermute_b32 v135, v145, v137
	v_mov_b32_e32 v133, v137
	s_waitcnt lgkmcnt(0)
	v_pk_add_f32 v[132:133], v[132:133], v[134:135]
	ds_bpermute_b32 v134, v144, v132
	ds_bpermute_b32 v135, v144, v133
	s_and_saveexec_b64 s[0:1], vcc
	s_cbranch_execz .LBB0_271
	v_lshl_or_b32 v136, v136, 5, v128
	s_waitcnt lgkmcnt(0)
	v_pk_add_f32 v[132:133], v[132:133], v[134:135]
	ds_write_b64 v136, v[132:133]
.LBB0_271:
	s_or_b64 exec, exec, s[0:1]
	v_add_u32_e32 v136, 0x90, v157
	v_add_u32_e32 v132, s91, v136
	v_ashrrev_i32_e32 v133, 31, v132
	v_lshlrev_b64 v[132:133], 12, v[132:133]
	s_waitcnt lgkmcnt(0)
	v_lshl_add_u64 v[134:135], v[130:131], 0, v[132:133]
	s_waitcnt vmcnt(0)
	v_mov_b32_e32 v132, v210
	v_mov_b32_e32 v133, v211
	s_waitcnt vmcnt(0)
	v_lshlrev_b32_e32 v138, 16, v132
	v_and_b32_e32 v139, 0xffff0000, v132
	v_lshlrev_b32_e32 v132, 16, v133
	v_and_b32_e32 v133, 0xffff0000, v133
	v_pk_fma_f32 v[44:45], v[138:139], s[80:81], v[44:45] op_sel_hi:[1,0,1]
	v_pk_fma_f32 v[46:47], v[132:133], s[80:81], v[46:47] op_sel_hi:[1,0,1]
	v_mov_b32_e32 v132, v44
	v_mov_b32_e32 v133, v46
	v_mov_b32_e32 v138, v45
	v_mov_b32_e32 v139, v47
	v_pk_add_f32 v[132:133], v[132:133], v[138:139]
	s_waitcnt vmcnt(0)
	v_mov_b32_e32 v138, v212
	v_mov_b32_e32 v139, v213
	v_fma_f32 v137, v47, v47, 0
	v_fmac_f32_e32 v137, v46, v46
	v_fmac_f32_e32 v137, v45, v45
	v_fmac_f32_e32 v137, v44, v44
	v_add_f32_e32 v132, v132, v133
	v_add_f32_e32 v132, 0, v132
	s_waitcnt vmcnt(0)
	v_lshlrev_b32_e32 v140, 16, v138
	v_and_b32_e32 v141, 0xffff0000, v138
	v_lshlrev_b32_e32 v138, 16, v139
	v_and_b32_e32 v139, 0xffff0000, v139
	v_pk_fma_f32 v[40:41], v[140:141], s[80:81], v[40:41] op_sel_hi:[1,0,1]
	v_pk_fma_f32 v[42:43], v[138:139], s[80:81], v[42:43] op_sel_hi:[1,0,1]
	v_mov_b32_e32 v138, v40
	v_mov_b32_e32 v139, v42
	v_mov_b32_e32 v140, v41
	v_mov_b32_e32 v141, v43
	v_pk_add_f32 v[138:139], v[138:139], v[140:141]
	s_waitcnt vmcnt(0)
	v_mov_b32_e32 v140, v214
	v_mov_b32_e32 v141, v215
	v_fmac_f32_e32 v137, v43, v43
	s_waitcnt vmcnt(0)
	v_mov_b32_e32 v134, v216
	v_mov_b32_e32 v135, v217
	v_fmac_f32_e32 v137, v42, v42
	v_fmac_f32_e32 v137, v41, v41
	v_fmac_f32_e32 v137, v40, v40
	v_pk_add_f32 v[138:139], v[138:139], v[138:139] op_sel:[0,1] op_sel_hi:[1,0]
	s_waitcnt vmcnt(1)
	v_lshlrev_b32_e32 v142, 16, v140
	v_and_b32_e32 v143, 0xffff0000, v140
	v_lshlrev_b32_e32 v140, 16, v141
	v_and_b32_e32 v141, 0xffff0000, v141
	v_pk_fma_f32 v[38:39], v[140:141], s[80:81], v[38:39] op_sel_hi:[1,0,1]
	v_pk_fma_f32 v[36:37], v[142:143], s[80:81], v[36:37] op_sel_hi:[1,0,1]
	v_fmac_f32_e32 v137, v39, v39
	v_fmac_f32_e32 v137, v38, v38
	v_fmac_f32_e32 v137, v37, v37
	s_waitcnt vmcnt(0)
	v_lshlrev_b32_e32 v150, 16, v134
	v_and_b32_e32 v151, 0xffff0000, v134
	v_lshlrev_b32_e32 v134, 16, v135
	v_and_b32_e32 v135, 0xffff0000, v135
	v_pk_add_f32 v[140:141], v[36:37], v[36:37] op_sel:[0,1] op_sel_hi:[1,0]
	v_pk_add_f32 v[142:143], v[38:39], v[38:39] op_sel:[0,1] op_sel_hi:[1,0]
	v_fmac_f32_e32 v137, v36, v36
	v_pk_fma_f32 v[32:33], v[150:151], s[80:81], v[32:33] op_sel_hi:[1,0,1]
	v_pk_fma_f32 v[34:35], v[134:135], s[80:81], v[34:35] op_sel_hi:[1,0,1]
	v_mov_b32_e32 v133, v32
	v_mov_b32_e32 v139, v33
	v_mov_b32_e32 v141, v34
	v_mov_b32_e32 v143, v35
	v_fmac_f32_e32 v137, v35, v35
	v_pk_add_f32 v[132:133], v[132:133], v[138:139]
	v_pk_add_f32 v[134:135], v[140:141], v[142:143]
	v_fmac_f32_e32 v137, v34, v34
	v_pk_add_f32 v[132:133], v[132:133], v[134:135]
	v_fmac_f32_e32 v137, v33, v33
	v_pk_add_f32 v[132:133], v[132:133], v[132:133] op_sel:[0,1] op_sel_hi:[1,0]
	v_fmac_f32_e32 v137, v32, v32
	ds_bpermute_b32 v134, v145, v132
	ds_bpermute_b32 v135, v145, v137
	v_mov_b32_e32 v133, v137
	s_waitcnt lgkmcnt(0)
	v_pk_add_f32 v[132:133], v[132:133], v[134:135]
	ds_bpermute_b32 v134, v144, v132
	ds_bpermute_b32 v135, v144, v133
	s_and_saveexec_b64 s[0:1], vcc
	s_cbranch_execz .LBB0_273
	v_lshl_or_b32 v136, v136, 5, v128
	s_waitcnt lgkmcnt(0)
	v_pk_add_f32 v[132:133], v[132:133], v[134:135]
	ds_write_b64 v136, v[132:133]
.LBB0_273:
	s_or_b64 exec, exec, s[0:1]
	v_add_u32_e32 v136, 0xa0, v157
	v_add_u32_e32 v132, s91, v136
	v_ashrrev_i32_e32 v133, 31, v132
	v_lshlrev_b64 v[132:133], 12, v[132:133]
	v_lshl_add_u64 v[138:139], v[130:131], 0, v[132:133]
	s_waitcnt vmcnt(0)
	v_mov_b32_e32 v132, v218
	v_mov_b32_e32 v133, v219
	s_waitcnt vmcnt(0) lgkmcnt(1)
	v_lshlrev_b32_e32 v134, 16, v132
	s_waitcnt lgkmcnt(0)
	v_and_b32_e32 v135, 0xffff0000, v132
	v_lshlrev_b32_e32 v140, 16, v133
	v_and_b32_e32 v141, 0xffff0000, v133
	v_pk_fma_f32 v[132:133], v[134:135], s[80:81], v[28:29] op_sel_hi:[1,0,1]
	v_pk_fma_f32 v[134:135], v[140:141], s[80:81], v[30:31] op_sel_hi:[1,0,1]
	v_mov_b32_e32 v28, v132
	v_mov_b32_e32 v29, v134
	v_mov_b32_e32 v30, v133
	v_mov_b32_e32 v31, v135
	v_pk_add_f32 v[28:29], v[28:29], v[30:31]
	s_waitcnt vmcnt(0)
	v_mov_b32_e32 v30, v220
	v_mov_b32_e32 v31, v221
	v_fma_f32 v137, v135, v135, 0
	v_fmac_f32_e32 v137, v134, v134
	v_fmac_f32_e32 v137, v133, v133
	v_fmac_f32_e32 v137, v132, v132
	v_add_f32_e32 v28, v28, v29
	v_add_f32_e32 v28, 0, v28
	s_waitcnt vmcnt(0)
	v_lshlrev_b32_e32 v140, 16, v30
	v_and_b32_e32 v141, 0xffff0000, v30
	v_lshlrev_b32_e32 v30, 16, v31
	v_and_b32_e32 v31, 0xffff0000, v31
	v_pk_fma_f32 v[24:25], v[140:141], s[80:81], v[24:25] op_sel_hi:[1,0,1]
	v_pk_fma_f32 v[26:27], v[30:31], s[80:81], v[26:27] op_sel_hi:[1,0,1]
	v_mov_b32_e32 v30, v24
	v_mov_b32_e32 v31, v26
	v_mov_b32_e32 v140, v25
	v_mov_b32_e32 v141, v27
	v_pk_add_f32 v[30:31], v[30:31], v[140:141]
	s_waitcnt vmcnt(0)
	v_mov_b32_e32 v140, v222
	v_mov_b32_e32 v141, v223
	v_fmac_f32_e32 v137, v27, v27
	s_waitcnt vmcnt(0)
	v_mov_b32_e32 v138, v224
	v_mov_b32_e32 v139, v225
	v_fmac_f32_e32 v137, v26, v26
	v_fmac_f32_e32 v137, v25, v25
	v_fmac_f32_e32 v137, v24, v24
	v_pk_add_f32 v[30:31], v[30:31], v[30:31] op_sel:[0,1] op_sel_hi:[1,0]
	s_waitcnt vmcnt(1)
	v_lshlrev_b32_e32 v142, 16, v140
	v_and_b32_e32 v143, 0xffff0000, v140
	v_lshlrev_b32_e32 v140, 16, v141
	v_and_b32_e32 v141, 0xffff0000, v141
	v_pk_fma_f32 v[22:23], v[140:141], s[80:81], v[22:23] op_sel_hi:[1,0,1]
	v_pk_fma_f32 v[20:21], v[142:143], s[80:81], v[20:21] op_sel_hi:[1,0,1]
	v_fmac_f32_e32 v137, v23, v23
	v_fmac_f32_e32 v137, v22, v22
	v_fmac_f32_e32 v137, v21, v21
	s_waitcnt vmcnt(0)
	v_lshlrev_b32_e32 v150, 16, v138
	v_and_b32_e32 v151, 0xffff0000, v138
	v_lshlrev_b32_e32 v138, 16, v139
	v_and_b32_e32 v139, 0xffff0000, v139
	v_pk_add_f32 v[140:141], v[20:21], v[20:21] op_sel:[0,1] op_sel_hi:[1,0]
	v_pk_add_f32 v[142:143], v[22:23], v[22:23] op_sel:[0,1] op_sel_hi:[1,0]
	v_fmac_f32_e32 v137, v20, v20
	v_pk_fma_f32 v[16:17], v[150:151], s[80:81], v[16:17] op_sel_hi:[1,0,1]
	v_pk_fma_f32 v[18:19], v[138:139], s[80:81], v[18:19] op_sel_hi:[1,0,1]
	v_mov_b32_e32 v29, v16
	v_mov_b32_e32 v31, v17
	v_mov_b32_e32 v141, v18
	v_mov_b32_e32 v143, v19
	v_fmac_f32_e32 v137, v19, v19
	v_pk_add_f32 v[28:29], v[28:29], v[30:31]
	v_pk_add_f32 v[30:31], v[140:141], v[142:143]
	v_fmac_f32_e32 v137, v18, v18
	v_pk_add_f32 v[28:29], v[28:29], v[30:31]
	v_fmac_f32_e32 v137, v17, v17
	v_pk_add_f32 v[28:29], v[28:29], v[28:29] op_sel:[0,1] op_sel_hi:[1,0]
	v_fmac_f32_e32 v137, v16, v16
	ds_bpermute_b32 v30, v145, v28
	ds_bpermute_b32 v31, v145, v137
	v_mov_b32_e32 v29, v137
	s_waitcnt lgkmcnt(0)
	v_pk_add_f32 v[28:29], v[28:29], v[30:31]
	ds_bpermute_b32 v30, v144, v28
	ds_bpermute_b32 v31, v144, v29
	s_and_saveexec_b64 s[0:1], vcc
	s_cbranch_execz .LBB0_275
	v_lshl_or_b32 v136, v136, 5, v128
	s_waitcnt lgkmcnt(0)
	v_pk_add_f32 v[28:29], v[28:29], v[30:31]
	ds_write_b64 v136, v[28:29]
.LBB0_275:
	s_or_b64 exec, exec, s[0:1]
	v_add_u32_e32 v146, 0xb0, v157
	v_add_u32_e32 v28, s91, v146
	v_ashrrev_i32_e32 v29, 31, v28
	v_lshlrev_b64 v[28:29], 12, v[28:29]
	v_lshl_add_u64 v[150:151], v[130:131], 0, v[28:29]
	s_waitcnt vmcnt(0)
	v_mov_b32_e32 v28, v226
	v_mov_b32_e32 v29, v227
	s_waitcnt vmcnt(0) lgkmcnt(1)
	v_lshlrev_b32_e32 v30, 16, v28
	s_waitcnt lgkmcnt(0)
	v_and_b32_e32 v31, 0xffff0000, v28
	v_lshlrev_b32_e32 v28, 16, v29
	v_and_b32_e32 v29, 0xffff0000, v29
	v_pk_fma_f32 v[138:139], v[30:31], s[80:81], v[12:13] op_sel_hi:[1,0,1]
	v_pk_fma_f32 v[140:141], v[28:29], s[80:81], v[14:15] op_sel_hi:[1,0,1]
	v_mov_b32_e32 v12, v138
	v_mov_b32_e32 v13, v140
	v_mov_b32_e32 v14, v139
	v_mov_b32_e32 v15, v141
	v_pk_add_f32 v[12:13], v[12:13], v[14:15]
	v_fma_f32 v164, v141, v141, 0
	v_add_f32_e32 v12, v12, v13
	v_add_f32_e32 v142, 0, v12
	s_waitcnt vmcnt(0)
	v_mov_b32_e32 v12, v228
	v_mov_b32_e32 v13, v229
	v_fmac_f32_e32 v164, v140, v140
	v_fmac_f32_e32 v164, v139, v139
	v_fmac_f32_e32 v164, v138, v138
	s_waitcnt vmcnt(0)
	v_lshlrev_b32_e32 v14, 16, v12
	v_and_b32_e32 v15, 0xffff0000, v12
	v_lshlrev_b32_e32 v12, 16, v13
	v_and_b32_e32 v13, 0xffff0000, v13
	v_pk_fma_f32 v[130:131], v[14:15], s[80:81], v[8:9] op_sel_hi:[1,0,1]
	v_pk_fma_f32 v[136:137], v[12:13], s[80:81], v[10:11] op_sel_hi:[1,0,1]
	v_mov_b32_e32 v8, v130
	v_mov_b32_e32 v9, v136
	v_mov_b32_e32 v10, v131
	v_mov_b32_e32 v11, v137
	v_pk_add_f32 v[8:9], v[8:9], v[10:11]
	s_waitcnt vmcnt(0)
	v_mov_b32_e32 v10, v230
	v_mov_b32_e32 v11, v231
	v_fmac_f32_e32 v164, v137, v137
	v_fmac_f32_e32 v164, v136, v136
	v_fmac_f32_e32 v164, v131, v131
	v_fmac_f32_e32 v164, v130, v130
	v_pk_add_f32 v[8:9], v[8:9], v[8:9] op_sel:[0,1] op_sel_hi:[1,0]
	s_waitcnt vmcnt(0)
	v_lshlrev_b32_e32 v12, 16, v10
	v_and_b32_e32 v13, 0xffff0000, v10
	v_lshlrev_b32_e32 v10, 16, v11
	v_and_b32_e32 v11, 0xffff0000, v11
	v_pk_fma_f32 v[30:31], v[10:11], s[80:81], v[6:7] op_sel_hi:[1,0,1]
	s_waitcnt vmcnt(0)
	v_mov_b32_e32 v10, v232
	v_mov_b32_e32 v11, v233
	v_fmac_f32_e32 v164, v31, v31
	v_pk_fma_f32 v[28:29], v[12:13], s[80:81], v[4:5] op_sel_hi:[1,0,1]
	v_fmac_f32_e32 v164, v30, v30
	v_fmac_f32_e32 v164, v29, v29
	v_pk_add_f32 v[4:5], v[28:29], v[28:29] op_sel:[0,1] op_sel_hi:[1,0]
	v_pk_add_f32 v[6:7], v[30:31], v[30:31] op_sel:[0,1] op_sel_hi:[1,0]
	v_fmac_f32_e32 v164, v28, v28
	s_waitcnt vmcnt(0)
	v_lshlrev_b32_e32 v12, 16, v10
	v_and_b32_e32 v13, 0xffff0000, v10
	v_lshlrev_b32_e32 v10, 16, v11
	v_and_b32_e32 v11, 0xffff0000, v11
	v_pk_fma_f32 v[12:13], v[12:13], s[80:81], v[0:1] op_sel_hi:[1,0,1]
	v_pk_fma_f32 v[14:15], v[10:11], s[80:81], v[2:3] op_sel_hi:[1,0,1]
	v_mov_b32_e32 v143, v12
	v_mov_b32_e32 v9, v13
	v_mov_b32_e32 v5, v14
	v_mov_b32_e32 v7, v15
	v_fmac_f32_e32 v164, v15, v15
	v_pk_add_f32 v[0:1], v[142:143], v[8:9]
	v_pk_add_f32 v[2:3], v[4:5], v[6:7]
	v_fmac_f32_e32 v164, v14, v14
	v_pk_add_f32 v[0:1], v[0:1], v[2:3]
	v_fmac_f32_e32 v164, v13, v13
	v_pk_add_f32 v[0:1], v[0:1], v[0:1] op_sel:[0,1] op_sel_hi:[1,0]
	v_fmac_f32_e32 v164, v12, v12
	ds_bpermute_b32 v2, v145, v0
	ds_bpermute_b32 v3, v145, v164
	v_mov_b32_e32 v1, v164
	s_waitcnt lgkmcnt(0)
	v_pk_add_f32 v[0:1], v[0:1], v[2:3]
	ds_bpermute_b32 v2, v144, v0
	ds_bpermute_b32 v3, v144, v1
	s_and_saveexec_b64 s[0:1], vcc
	s_cbranch_execz .LBB0_277
	v_lshl_or_b32 v4, v146, 5, v128
	s_waitcnt lgkmcnt(0)
	v_pk_add_f32 v[0:1], v[0:1], v[2:3]
	ds_write_b64 v4, v[0:1]

.LBB0_290:
	s_or_b64 exec, exec, s[0:1]
	s_barrier
	s_and_saveexec_b64 s[0:1], s[4:5]
	s_cbranch_execz .LBB0_292
	global_load_dwordx2 v[170:171], v[0:1], off sc1
	global_load_dwordx2 v[172:173], v[0:1], off offset:8 sc1
	global_load_dwordx2 v[174:175], v[0:1], off offset:16 sc1
	global_load_dwordx2 v[176:177], v[0:1], off offset:24 sc1
	global_load_dwordx2 v[178:179], v[0:1], off offset:32 sc1
	global_load_dwordx2 v[180:181], v[0:1], off offset:40 sc1
	global_load_dwordx2 v[182:183], v[0:1], off offset:48 sc1
	global_load_dwordx2 v[184:185], v[0:1], off offset:56 sc1
	s_mov_b32 s2, 0x3a000000
	s_waitcnt vmcnt(0)
	v_add_f32_e32 v4, 0, v170
	v_add_f32_e32 v5, 0, v171
	v_add_f32_e32 v4, v4, v172
	v_add_f32_e32 v5, v5, v173
	v_add_f32_e32 v4, v4, v174
	v_add_f32_e32 v5, v5, v175
	v_add_f32_e32 v4, v4, v176
	v_add_f32_e32 v5, v5, v177
	v_add_f32_e32 v4, v4, v178
	v_add_f32_e32 v5, v5, v179
	v_add_f32_e32 v4, v4, v180
	v_add_f32_e32 v5, v5, v181
	v_add_f32_e32 v2, v4, v182
	v_add_f32_e32 v3, v5, v183
	v_add_f32_e32 v0, v2, v184
	v_mul_f32_e32 v0, 0x3a000000, v0
	v_add_f32_e32 v1, v3, v185
	v_mul_f32_e32 v2, v0, v0
	v_fma_f32 v1, v1, s2, -v2
	v_max_f32_e32 v1, 0, v1
	v_add_f32_e32 v1, 0x3727c5ac, v1
	s_mov_b32 s2, 0x800000
	v_cmp_gt_f32_e32 vcc, s2, v1
	v_mul_f32_e32 v2, 0x4b800000, v1
	s_nop 0
	v_cndmask_b32_e32 v1, v1, v2, vcc
	v_rsq_f32_e32 v1, v1
	s_nop 0
	v_mul_f32_e32 v2, 0x45800000, v1
	v_cndmask_b32_e32 v1, v1, v2, vcc
	v_lshlrev_b32_e32 v2, 3, v158
	ds_write_b64 v2, v[0:1] offset:8192
